# v012 + MoBA gate-score loop: software-prefetch the next 16-byte q chunk one iteration ahead
# speedup vs baseline: 1.0460x; 1.0043x over previous
; #define LAS __attribute__((address_space(3)))
; __device__ __forceinline__ float bf2f(unsigned h) { return __uint_as_float(h << 16); }
; __device__ __forceinline__ void moba_unit(const int wv, LAS unsigned char* lds, int b, int h, int qb, const bf16* Y, const float* kmean_l, bf16* OG) {
;     ...
;     { const float* src = kmean_l + (size_t)(b * NH + h) * 16 * 64; km[tid] = src[tid]; km[tid + 512] = src[tid + 512]; }
;     __syncthreads();
;     {
;         const int ql = tid >> 1, half = tid & 1;
;         const bf16* qrow = Y + (rowblk + ql) * MOBA_LDY + h * 64;
;         float g[8];
; #pragma unroll
;         for (int n = 0; n < 8; ++n) g[n] = 0.f;
; #pragma unroll 1
;         for (int c = 0; c < 8; ++c) {
;             const v4u qv = *(const v4u*)(qrow + 8 * c);
;             float qf[8] = {bf2f(qv.x & 0xffffu), bf2f(qv.x >> 16), bf2f(qv.y & 0xffffu), bf2f(qv.y >> 16), bf2f(qv.z & 0xffffu), bf2f(qv.z >> 16), bf2f(qv.w & 0xffffu), bf2f(qv.w >> 16)};
; #pragma unroll
;             for (int n = 0; n < 8; ++n) {
;                 const LAS f32x4* kr = (const LAS f32x4*)(km + (8 * half + n) * 64 + 8 * c);
;                 const f32x4 k0 = kr[0], k1 = kr[1];
;                 g[n] += (qf[0] * k0[0] + qf[1] * k0[1]) + (qf[2] * k0[2] + qf[3] * k0[3]) + (qf[4] * k1[0] + qf[5] * k1[1]) + (qf[6] * k1[2] + qf[7] * k1[3]);
;             }
;         }
.LBB0_1156:
	s_lshl_b32 s0, s23, 1
	s_and_b32 s4, s0, 0x780
	s_lshl_b32 s0, s27, 1
	s_add_i32 s12, s3, s0
	s_bitcmp0_b32 s27, 0
	s_cselect_b32 s33, s22, s2
	s_ashr_i32 s8, s12, 4
	s_ashr_i32 s9, s8, 31
	s_lshl_b64 s[10:11], s[8:9], 12
	s_lshl_b32 s0, s33, 8
	s_ashr_i32 s13, s12, 31
	s_or_b32 s10, s10, s0
	s_lshl_b64 s[0:1], s[12:13], 12
	v_readlane_b32 s5, v254, 29
	v_mbcnt_lo_u32_b32 v12, -1, 0
	v_mbcnt_hi_u32_b32 v12, -1, v12
	s_add_u32 s0, s5, s0
	v_add_u32_e32 v0, s83, v12
	v_readlane_b32 s5, v254, 30
	s_addc_u32 s1, s5, s1
	v_ashrrev_i32_e32 v1, 31, v0
	v_lshl_add_u64 v[2:3], v[0:1], 2, s[0:1]
	global_load_dword v1, v[2:3], off
	v_lshl_add_u32 v4, v0, 2, 0
	global_load_dword v2, v[2:3], off offset:2048
	v_add_u32_e32 v4, 0x11000, v4
	v_ashrrev_i32_e32 v0, 1, v0
	v_readlane_b32 s0, v254, 27
	v_readlane_b32 s1, v254, 28
	s_add_u32 s0, s0, s4
	s_addc_u32 s1, s1, 0
	v_mov_b32_e32 v10, 0
	v_mov_b32_e32 v11, v10
	v_mov_b32_e32 v8, v10
	v_mov_b32_e32 v9, v10
	v_mov_b32_e32 v5, v10
	s_waitcnt vmcnt(0)
	ds_write2st64_b32 v4, v1, v2 offset1:8
	v_ashrrev_i32_e32 v1, 31, v0
	v_lshl_add_u64 v[2:3], s[10:11], 0, v[0:1]
	v_lshlrev_b64 v[2:3], 13, v[2:3]
	v_and_b32_e32 v1, 1, v12
	v_lshl_add_u32 v13, v1, 11, 0
	v_lshl_add_u64 v[6:7], s[0:1], 0, v[2:3]
	s_mov_b32 s0, 0
	v_mov_b32_e32 v4, v10
	v_mov_b32_e32 v2, v10
	v_mov_b32_e32 v3, v10
	global_load_dwordx4 v[56:59], v[6:7], off
	v_lshl_add_u64 v[6:7], v[6:7], 0, 16
	s_waitcnt lgkmcnt(0)
	s_barrier
.LBB0_1157:
	s_waitcnt vmcnt(0)
	v_mov_b32_e32 v14, v56
	v_mov_b32_e32 v15, v57
	v_mov_b32_e32 v16, v58
	v_mov_b32_e32 v17, v59
	s_cmpk_eq_i32 s0, 0xe0
	s_cbranch_scc1 .Lgate_pf_skip
	global_load_dwordx4 v[56:59], v[6:7], off
.Lgate_pf_skip:
	v_add_u32_e32 v48, s0, v13
	v_add_u32_e32 v18, 0x11000, v48
	v_add_u32_e32 v26, 0x11100, v48
	ds_read_b128 v[18:21], v18
	ds_read_b128 v[26:29], v26
	v_add_u32_e32 v22, 0x11010, v48
	v_add_u32_e32 v30, 0x11110, v48
	ds_read_b128 v[22:25], v22
	ds_read_b128 v[30:33], v30
	s_add_i32 s0, s0, 32
	v_lshl_add_u64 v[6:7], v[6:7], 0, 16
	s_cmpk_eq_i32 s0, 0x100
	v_and_b32_e32 v35, 0xffff0000, v14
	v_and_b32_e32 v34, 16, v14
	v_lshlrev_b32_e32 v36, 16, v14
	v_mov_b32_e32 v37, v35
	v_and_b32_e32 v39, 0xffff0000, v15
	v_and_b32_e32 v45, 0xffff0000, v17
	v_and_b32_e32 v44, 16, v17
	v_lshlrev_b32_e32 v46, 16, v17
	s_waitcnt lgkmcnt(3)
	v_mov_b32_e32 v17, v19
	s_waitcnt lgkmcnt(2)
	v_pk_mov_b32 v[18:19], v[26:27], v[18:19] op_sel:[1,0]
	v_pk_mov_b32 v[34:35], v[34:35], v[36:37] op_sel:[1,0]
	v_and_b32_e32 v38, 16, v15
	v_lshlrev_b32_e32 v40, 16, v15
	v_mov_b32_e32 v41, v39
	v_and_b32_e32 v15, 0xffff0000, v16
	v_and_b32_e32 v14, 16, v16
	v_lshlrev_b32_e32 v42, 16, v16
	v_mov_b32_e32 v16, v26
	v_pk_mul_f32 v[18:19], v[18:19], v[34:35]
	v_pk_mov_b32 v[38:39], v[38:39], v[40:41] op_sel:[1,0]
	v_pk_fma_f32 v[16:17], v[16:17], v[36:37], v[18:19]
	v_mov_b32_e32 v19, v21
	v_pk_mov_b32 v[20:21], v[28:29], v[20:21] op_sel:[1,0]
	v_mov_b32_e32 v18, v28
	v_pk_mul_f32 v[20:21], v[20:21], v[38:39]
	v_mov_b32_e32 v43, v15
	v_pk_fma_f32 v[18:19], v[18:19], v[40:41], v[20:21]
	s_waitcnt lgkmcnt(0)
	v_pk_mov_b32 v[20:21], v[30:31], v[22:23] op_sel:[1,0]
	v_pk_add_f32 v[16:17], v[16:17], v[18:19]
	v_mov_b32_e32 v18, v30
	v_pk_mov_b32 v[30:31], v[14:15], v[42:43] op_sel:[1,0]
	v_mov_b32_e32 v19, v23
	v_pk_mul_f32 v[14:15], v[20:21], v[30:31]
	v_mov_b32_e32 v47, v45
	v_pk_fma_f32 v[14:15], v[18:19], v[42:43], v[14:15]
	v_pk_mov_b32 v[18:19], v[32:33], v[24:25] op_sel:[1,0]
	v_pk_add_f32 v[14:15], v[16:17], v[14:15]
	v_mov_b32_e32 v16, v32
	v_pk_mov_b32 v[32:33], v[44:45], v[46:47] op_sel:[1,0]
	v_mov_b32_e32 v17, v25
	v_pk_mul_f32 v[18:19], v[18:19], v[32:33]
	v_add_u32_e32 v22, 0x11300, v48
	v_pk_fma_f32 v[16:17], v[16:17], v[46:47], v[18:19]
	ds_read_b128 v[22:25], v22
	v_pk_add_f32 v[14:15], v[16:17], v[14:15]
	v_add_u32_e32 v18, 0x11210, v48
	v_pk_add_f32 v[10:11], v[10:11], v[14:15]
	v_add_u32_e32 v14, 0x11200, v48
	ds_read_b128 v[14:17], v14
	ds_read_b128 v[18:21], v18
	v_add_u32_e32 v26, 0x11310, v48
	ds_read_b128 v[26:29], v26
	s_waitcnt lgkmcnt(2)
	v_pk_mov_b32 v[44:45], v[14:15], v[22:23] op_sel:[1,0]
	v_mov_b32_e32 v15, v23
	v_pk_mov_b32 v[22:23], v[16:17], v[24:25] op_sel:[1,0]
	v_mov_b32_e32 v17, v25
	v_pk_mul_f32 v[14:15], v[14:15], v[36:37]
	v_pk_mul_f32 v[16:17], v[16:17], v[40:41]
	v_pk_fma_f32 v[14:15], v[44:45], v[34:35], v[14:15]
	v_pk_fma_f32 v[16:17], v[22:23], v[38:39], v[16:17]
	v_add_u32_e32 v22, 0x11500, v48
	v_pk_add_f32 v[14:15], v[14:15], v[16:17]
	s_waitcnt lgkmcnt(0)
; #define LAS __attribute__((address_space(3)))
; __device__ __forceinline__ void moba_unit(const int wv, LAS unsigned char* lds, int b, int h, int qb, const bf16* Y, const float* kmean_l, bf16* OG) {
;     ...
;             for (int n = 0; n < 8; ++n) {
;                 const LAS f32x4* kr = (const LAS f32x4*)(km + (8 * half + n) * 64 + 8 * c);
;                 const f32x4 k0 = kr[0], k1 = kr[1];
;                 g[n] += (qf[0] * k0[0] + qf[1] * k0[1]) + (qf[2] * k0[2] + qf[3] * k0[3]) + (qf[4] * k1[0] + qf[5] * k1[1]) + (qf[6] * k1[2] + qf[7] * k1[3]);
;             }
;         }
;         float ga[16];
; #pragma unroll
;         for (int n = 0; n < 8; ++n) { const float o = xshfl<1>(g[n]); ga[n] = half ? o : g[n]; ga[8 + n] = half ? g[n] : o; }
;         unsigned mask = 0u;
; #pragma unroll 1
;         for (int it = 0; it < 3; ++it) {
;             float best = -3.0e38f; int bi = -1;
; #pragma unroll
;             for (int n = 0; n < 16; ++n) { const bool ok = (n < qb) && !((mask >> n) & 1u); const float cand = ok ? ga[n] : -3.0e38f; if (cand > best) { best = cand; bi = n; } }
	v_pk_mov_b32 v[16:17], v[18:19], v[26:27] op_sel:[1,0]
	v_mov_b32_e32 v19, v27
	v_pk_mul_f32 v[18:19], v[18:19], v[42:43]
	ds_read_b128 v[22:25], v22
	v_pk_fma_f32 v[16:17], v[16:17], v[30:31], v[18:19]
	v_add_u32_e32 v26, 0x11510, v48
	v_pk_add_f32 v[14:15], v[14:15], v[16:17]
	v_pk_mov_b32 v[16:17], v[20:21], v[28:29] op_sel:[1,0]
	v_mov_b32_e32 v21, v29
	v_pk_mul_f32 v[18:19], v[20:21], v[46:47]
	ds_read_b128 v[26:29], v26
	v_pk_fma_f32 v[16:17], v[16:17], v[32:33], v[18:19]
	v_add_u32_e32 v18, 0x11410, v48
	v_pk_add_f32 v[14:15], v[16:17], v[14:15]
	ds_read_b128 v[18:21], v18
	v_pk_add_f32 v[8:9], v[8:9], v[14:15]
	v_add_u32_e32 v14, 0x11400, v48
	ds_read_b128 v[14:17], v14
	s_waitcnt lgkmcnt(0)
	v_pk_mov_b32 v[44:45], v[14:15], v[22:23] op_sel:[1,0]
	v_mov_b32_e32 v15, v23
	v_pk_mov_b32 v[22:23], v[16:17], v[24:25] op_sel:[1,0]
	v_mov_b32_e32 v17, v25
	v_pk_mul_f32 v[14:15], v[14:15], v[36:37]
	v_pk_mul_f32 v[16:17], v[16:17], v[40:41]
	v_pk_fma_f32 v[14:15], v[44:45], v[34:35], v[14:15]
	v_pk_fma_f32 v[16:17], v[22:23], v[38:39], v[16:17]
	v_add_u32_e32 v22, 0x11700, v48
	v_pk_add_f32 v[14:15], v[14:15], v[16:17]
	v_pk_mov_b32 v[16:17], v[18:19], v[26:27] op_sel:[1,0]
	v_mov_b32_e32 v19, v27
	v_pk_mul_f32 v[18:19], v[18:19], v[42:43]
	ds_read_b128 v[22:25], v22
	v_pk_fma_f32 v[16:17], v[16:17], v[30:31], v[18:19]
	v_add_u32_e32 v26, 0x11710, v48
	v_pk_add_f32 v[14:15], v[14:15], v[16:17]
	v_pk_mov_b32 v[16:17], v[20:21], v[28:29] op_sel:[1,0]
	v_mov_b32_e32 v21, v29
	v_pk_mul_f32 v[18:19], v[20:21], v[46:47]
	ds_read_b128 v[26:29], v26
	v_pk_fma_f32 v[16:17], v[16:17], v[32:33], v[18:19]
	v_add_u32_e32 v18, 0x11610, v48
	v_pk_add_f32 v[14:15], v[16:17], v[14:15]
	ds_read_b128 v[18:21], v18
	v_pk_add_f32 v[4:5], v[4:5], v[14:15]
	v_add_u32_e32 v14, 0x11600, v48
	ds_read_b128 v[14:17], v14
	s_waitcnt lgkmcnt(0)
	v_pk_mov_b32 v[44:45], v[14:15], v[22:23] op_sel:[1,0]
	v_mov_b32_e32 v15, v23
	v_pk_mov_b32 v[22:23], v[16:17], v[24:25] op_sel:[1,0]
	v_mov_b32_e32 v17, v25
	v_pk_mul_f32 v[14:15], v[14:15], v[36:37]
	v_pk_mul_f32 v[16:17], v[16:17], v[40:41]
	v_pk_fma_f32 v[14:15], v[44:45], v[34:35], v[14:15]
	v_pk_fma_f32 v[16:17], v[22:23], v[38:39], v[16:17]
	s_nop 0
	v_pk_add_f32 v[14:15], v[14:15], v[16:17]
	v_pk_mov_b32 v[16:17], v[18:19], v[26:27] op_sel:[1,0]
	v_mov_b32_e32 v19, v27
	v_pk_mul_f32 v[18:19], v[18:19], v[42:43]
	s_nop 0
	v_pk_fma_f32 v[16:17], v[16:17], v[30:31], v[18:19]
	s_nop 0
	v_pk_add_f32 v[14:15], v[14:15], v[16:17]
	v_pk_mov_b32 v[16:17], v[20:21], v[28:29] op_sel:[1,0]
	v_mov_b32_e32 v21, v29
	v_pk_mul_f32 v[18:19], v[20:21], v[46:47]
	s_nop 0
	v_pk_fma_f32 v[16:17], v[16:17], v[32:33], v[18:19]
	s_nop 0
	v_pk_add_f32 v[14:15], v[16:17], v[14:15]
	s_nop 0
	v_pk_add_f32 v[2:3], v[2:3], v[14:15]
	s_cbranch_scc0 .LBB0_1157
	ds_swizzle_b32 v6, v11 offset:swizzle(SWAP,1)
	s_cmp_lg_u32 s33, 0
	s_cselect_b64 s[4:5], -1, 0
	s_cmp_gt_u32 s33, 1
	s_cselect_b64 s[14:15], -1, 0
	s_cmp_gt_u32 s33, 2
	s_cselect_b64 s[16:17], -1, 0
	s_cmp_gt_u32 s33, 3
	v_cmp_eq_u32_e32 vcc, 0, v1
	s_cselect_b64 s[18:19], -1, 0
	s_cmp_gt_u32 s33, 4
	s_waitcnt lgkmcnt(0)
	v_cndmask_b32_e32 v1, v6, v11, vcc
	v_cndmask_b32_e32 v6, v11, v6, vcc
	ds_swizzle_b32 v11, v10 offset:swizzle(SWAP,1)
	ds_swizzle_b32 v13, v8 offset:swizzle(SWAP,1)
	ds_swizzle_b32 v14, v9 offset:swizzle(SWAP,1)
	ds_swizzle_b32 v15, v4 offset:swizzle(SWAP,1)
	ds_swizzle_b32 v16, v5 offset:swizzle(SWAP,1)
	ds_swizzle_b32 v17, v2 offset:swizzle(SWAP,1)
	s_cselect_b64 s[20:21], -1, 0
	s_cmp_gt_u32 s33, 5
	s_cselect_b64 s[30:31], -1, 0
	s_cmp_gt_u32 s33, 6
	s_cselect_b64 s[38:39], -1, 0
	s_cmp_gt_u32 s33, 7
	s_cselect_b64 s[40:41], -1, 0
	s_cmp_gt_u32 s33, 8
	s_cselect_b64 s[42:43], -1, 0
	s_cmp_gt_u32 s33, 9
	s_waitcnt lgkmcnt(5)
	v_cndmask_b32_e32 v7, v11, v10, vcc
	v_cndmask_b32_e32 v10, v10, v11, vcc
	s_waitcnt lgkmcnt(4)
	v_cndmask_b32_e32 v11, v13, v8, vcc
	v_cndmask_b32_e32 v8, v8, v13, vcc
	s_waitcnt lgkmcnt(3)
	v_cndmask_b32_e32 v13, v14, v9, vcc
	v_cndmask_b32_e32 v9, v9, v14, vcc
	s_waitcnt lgkmcnt(2)
	v_cndmask_b32_e32 v14, v15, v4, vcc
	v_cndmask_b32_e32 v4, v4, v15, vcc
	s_waitcnt lgkmcnt(1)
	v_cndmask_b32_e32 v15, v16, v5, vcc
	v_cndmask_b32_e32 v5, v5, v16, vcc
	s_waitcnt lgkmcnt(0)
	v_cndmask_b32_e32 v16, v17, v2, vcc
	v_cndmask_b32_e32 v2, v2, v17, vcc
	ds_swizzle_b32 v17, v3 offset:swizzle(SWAP,1)
	s_cselect_b64 s[44:45], -1, 0
	s_cmp_gt_u32 s33, 10
	s_cselect_b64 s[46:47], -1, 0
	s_cmp_gt_u32 s33, 11
	s_cselect_b64 s[48:49], -1, 0
	s_cmp_gt_u32 s33, 12
	s_cselect_b64 s[50:51], -1, 0
	s_cmp_gt_u32 s33, 13
	s_cselect_b64 s[52:53], -1, 0
	s_cmp_eq_u32 s33, 15
	s_waitcnt lgkmcnt(0)
	v_cndmask_b32_e32 v3, v17, v3, vcc
	s_mov_b32 s0, 3
	v_mov_b32_e32 v17, 0
	s_cselect_b64 s[54:55], -1, 0
	s_mov_b32 s1, 0xff61b1e6
